# prologue w_in transpose: 32 loads in flight per pass instead of one pair at a time
# speedup vs baseline: 1.0326x; 1.0169x over previous
; #define LAS __attribute__((address_space(3)))
; __device__ __forceinline__ void transpose_item(const float* W, int ldw, int K, bf16_t* WT, LAS float* scr, int kb, int nb, int srccol0, int lane, const float* gk) {
;     const int k0 = 64 * kb, n0 = 32 * nb;
; #pragma unroll 8
;     for (int i = 0; i < 32; ++i) { const int kk = 2 * i + (lane >> 5); scr[kk * 33 + (lane & 31)] = W[(size_t)(k0 + kk) * ldw + srccol0 + (lane & 31)] * (gk ? gk[k0 + kk] : 1.0f); }
;     asm volatile("s_waitcnt lgkmcnt(0)" ::: "memory");
.LBB0_17:
	v_lshl_add_u64 v[100:101], v[38:39], 0, s[18:19]
	global_load_dword v120, v[100:101], off
	v_lshl_add_u64 v[100:101], v[34:35], 0, s[18:19]
	global_load_dword v121, v[100:101], off
	v_lshl_add_u64 v[100:101], v[32:33], 0, s[18:19]
	global_load_dword v122, v[100:101], off
	v_lshl_add_u64 v[100:101], v[30:31], 0, s[18:19]
	global_load_dword v123, v[100:101], off
	v_lshl_add_u64 v[100:101], v[28:29], 0, s[18:19]
	global_load_dword v124, v[100:101], off
	v_lshl_add_u64 v[100:101], v[26:27], 0, s[18:19]
	global_load_dword v125, v[100:101], off
	v_lshl_add_u64 v[100:101], v[24:25], 0, s[18:19]
	global_load_dword v126, v[100:101], off
	v_lshl_add_u64 v[100:101], v[20:21], 0, s[18:19]
	global_load_dword v127, v[100:101], off
	s_add_u32 s18, s18, 0x40200
	s_addc_u32 s19, s19, 0
	v_lshl_add_u64 v[100:101], v[38:39], 0, s[18:19]
	global_load_dword v128, v[100:101], off
	v_lshl_add_u64 v[100:101], v[34:35], 0, s[18:19]
	global_load_dword v129, v[100:101], off
	v_lshl_add_u64 v[100:101], v[32:33], 0, s[18:19]
	global_load_dword v130, v[100:101], off
	v_lshl_add_u64 v[100:101], v[30:31], 0, s[18:19]
	global_load_dword v131, v[100:101], off
	v_lshl_add_u64 v[100:101], v[28:29], 0, s[18:19]
	global_load_dword v132, v[100:101], off
	v_lshl_add_u64 v[100:101], v[26:27], 0, s[18:19]
	global_load_dword v133, v[100:101], off
	v_lshl_add_u64 v[100:101], v[24:25], 0, s[18:19]
	global_load_dword v134, v[100:101], off
	v_lshl_add_u64 v[100:101], v[20:21], 0, s[18:19]
	global_load_dword v135, v[100:101], off
	v_mov_b32_e32 v152, 1.0
	v_mov_b32_e32 v153, 1.0
	v_mov_b32_e32 v154, 1.0
	v_mov_b32_e32 v155, 1.0
	v_mov_b32_e32 v156, 1.0
	v_mov_b32_e32 v157, 1.0
	v_mov_b32_e32 v158, 1.0
	v_mov_b32_e32 v159, 1.0
	v_mov_b32_e32 v160, 1.0
	v_mov_b32_e32 v161, 1.0
	v_mov_b32_e32 v162, 1.0
	v_mov_b32_e32 v163, 1.0
	v_mov_b32_e32 v164, 1.0
	v_mov_b32_e32 v165, 1.0
	v_mov_b32_e32 v166, 1.0
	v_mov_b32_e32 v167, 1.0
	s_andn2_b64 vcc, exec, s[12:13]
	s_cbranch_vccnz .Lpro_nogain
	v_lshl_add_u64 v[100:101], v[36:37], 0, s[16:17]
	global_load_dword v152, v[100:101], off
	global_load_dword v160, v[100:101], off offset:64
	v_lshl_add_u64 v[100:101], v[22:23], 0, s[16:17]
	global_load_dword v153, v[100:101], off offset:8
	global_load_dword v154, v[100:101], off offset:16
	global_load_dword v155, v[100:101], off offset:24
	global_load_dword v156, v[100:101], off offset:32
	global_load_dword v157, v[100:101], off offset:40
	global_load_dword v158, v[100:101], off offset:48
	global_load_dword v159, v[100:101], off offset:56
	global_load_dword v161, v[100:101], off offset:72
	global_load_dword v162, v[100:101], off offset:80
	global_load_dword v163, v[100:101], off offset:88
	global_load_dword v164, v[100:101], off offset:96
	global_load_dword v165, v[100:101], off offset:104
	global_load_dword v166, v[100:101], off offset:112
	global_load_dword v167, v[100:101], off offset:120
.Lpro_nogain:
	s_waitcnt vmcnt(0)
	v_mul_f32_e32 v120, v120, v152
	v_mul_f32_e32 v121, v121, v153
	v_mul_f32_e32 v122, v122, v154
	v_mul_f32_e32 v123, v123, v155
	v_mul_f32_e32 v124, v124, v156
	v_mul_f32_e32 v125, v125, v157
	v_mul_f32_e32 v126, v126, v158
	v_mul_f32_e32 v127, v127, v159
	v_mul_f32_e32 v128, v128, v160
	v_mul_f32_e32 v129, v129, v161
	v_mul_f32_e32 v130, v130, v162
	v_mul_f32_e32 v131, v131, v163
	v_mul_f32_e32 v132, v132, v164
	v_mul_f32_e32 v133, v133, v165
	v_mul_f32_e32 v134, v134, v166
	v_mul_f32_e32 v135, v135, v167
	ds_write_b32 v9, v120
	ds_write_b32 v9, v121 offset:264
	ds_write_b32 v9, v122 offset:528
	ds_write_b32 v9, v123 offset:792
	ds_write_b32 v9, v124 offset:1056
	ds_write_b32 v9, v125 offset:1320
	ds_write_b32 v9, v126 offset:1584
	ds_write_b32 v9, v127 offset:1848
	ds_write_b32 v9, v128 offset:2112
	ds_write_b32 v9, v129 offset:2376
	ds_write_b32 v9, v130 offset:2640
	ds_write_b32 v9, v131 offset:2904
	ds_write_b32 v9, v132 offset:3168
	ds_write_b32 v9, v133 offset:3432
	ds_write_b32 v9, v134 offset:3696
	ds_write_b32 v9, v135 offset:3960
	s_add_u32 s18, s18, 0x40200
	s_addc_u32 s19, s19, 0
	v_add_u32_e32 v9, 0x1080, v9
	v_lshl_add_u64 v[22:23], v[22:23], 0, 64
	v_lshl_add_u64 v[22:23], v[22:23], 0, 64
	s_cmp_lg_u32 s18, 0x100800
	v_lshl_add_u64 v[36:37], v[36:37], 0, 64
	v_lshl_add_u64 v[36:37], v[36:37], 0, 64
	s_cbranch_scc1 .LBB0_17
	s_branch .LBB0_8
